# XCD-local barriers now actually active: co-location check accepts any bijection logical-XCD -> XCC_ID (per-group OR masks) instead of identity; 4 seams use the per-XCC arrival counter, no L2 writeback
# speedup vs baseline: 1.0228x; 1.0212x over previous
; #define LAS __attribute__((address_space(3)))
; __device__ __forceinline__ unsigned xb_add(unsigned* p, unsigned v) { return __hip_atomic_fetch_add(p, v, __ATOMIC_RELAXED, __HIP_MEMORY_SCOPE_AGENT); }
; __device__ __forceinline__ unsigned xb_xcc_id() { return (unsigned)__builtin_amdgcn_s_getreg((3 << 11) | 20) & 0xFu; }
; __device__ __forceinline__ XcdBarrier xcd_barrier_post(unsigned* bar, volatile LAS unsigned* st) {
;     XcdBarrier b; b.bar = bar; b.x = xb_xcc_id(); b.st = st;
;     if (threadIdx.x == 0) (void)xb_add(&bar[XB_XCNT(b.x)], 1u);
;     return b;
; }
.LBB0_2:
	s_load_dwordx2 s[92:93], s[0:1], 0x90
	s_load_dwordx4 s[88:91], s[0:1], 0x80
	v_and_b32_e32 v200, 0x3ff, v0
	v_cmp_gt_u32_e32 vcc, 2, v200
	s_and_saveexec_b64 s[2:3], vcc
	v_lshl_add_u32 v1, v200, 2, 0
	v_add_u32_e32 v1, 0x24040, v1
	v_mov_b32_e32 v2, 0
	ds_write_b32 v1, v2
	s_or_b64 exec, exec, s[2:3]
	s_waitcnt lgkmcnt(0)
	s_add_u32 s2, s90, 0x70000
	s_addc_u32 s3, s91, 0
	v_writelane_b32 v254, s2, 2
	s_barrier
	s_nop 0
	v_writelane_b32 v254, s3, 3
	s_getreg_b32 s2, hwreg(HW_REG_XCC_ID, 0, 4)
	s_and_b32 s2, s2, 15
	v_writelane_b32 v254, s2, 4
	v_cmp_eq_u32_e64 s[4:5], 0, v200
	s_mov_b64 s[2:3], exec
	s_nop 0
	v_writelane_b32 v254, s4, 5
	s_nop 1
	v_writelane_b32 v254, s5, 6
	s_and_b64 s[4:5], s[2:3], s[4:5]
	s_mov_b64 exec, s[4:5]
	s_cbranch_execz .LBB0_7
	s_mov_b64 s[4:5], exec
	v_mbcnt_lo_u32_b32 v1, s4, 0
	v_mbcnt_hi_u32_b32 v1, s5, v1
	v_cmp_eq_u32_e32 vcc, 0, v1
	s_and_b64 s[6:7], exec, vcc
	s_mov_b64 exec, s[6:7]
	s_cbranch_execz .LBB0_7
	v_readlane_b32 s6, v254, 4
	s_bcnt1_i32_b64 s4, s[4:5]
	s_lshl_b32 s6, s6, 8
	v_mov_b32_e32 v2, s4
	v_readlane_b32 s4, v254, 2
	v_mov_b32_e32 v1, s6
	v_readlane_b32 s5, v254, 3
	s_nop 4
	global_atomic_add v1, v2, s[4:5] offset:1024
	s_lshr_b32 s6, s6, 8
	s_lshl_b32 s6, 1, s6
	s_cmp_lg_u32 s83, 0x100
	s_cselect_b32 s7, 0x30000, 0
	s_or_b32 s6, s6, s7
	s_and_b32 s7, s80, 7
	s_lshl_b32 s7, s7, 2
	s_add_i32 s7, s7, 0x3800
	v_mov_b32_e32 v3, s7
	v_mov_b32_e32 v4, s6
	global_atomic_or v3, v4, s[4:5]

; __device__ __forceinline__ void xcd_barrier(const XcdBarrier& b) {
;     ...
;         }
;     }
;     __syncthreads();
.LBB0_338:
	s_or_b64 exec, exec, s[2:3]
	s_waitcnt lgkmcnt(0)
	s_barrier
	v_mov_b32_e32 v245, 0x73800
	global_load_dwordx4 v[246:249], v245, s[90:91] sc1
	global_load_dwordx4 v[250:253], v245, s[90:91] offset:16 sc1

; #define PG8_STAGE(bufoff, gbase, voff) do { _Pragma("unroll") for (int _i = 0; _i < 2; ++_i) \
;         __builtin_amdgcn_global_load_lds((const unsigned*)((const char*)(gbase) + (voff)[_i]), (PG8_LAS unsigned*)(lds + (bufoff) + ldsw + _i * 8192), 16, 0, 0); } while (0)
; #define PG8_WAIT_V(n) asm volatile("s_waitcnt vmcnt(" #n ")" ::: "memory")
; #define PG8_BAR __builtin_amdgcn_s_barrier()
; template <class Epi, class Sched, bool ALIGN_EPI = false, bool SP2 = false>
; __device__ __forceinline__ void gemm_phase(PG8_LAS unsigned char* lds, const Gemm g, const Sched& S, const Epi& E) {
;     ...
;         PG8_STAGE(PG8_SB(1, 0), cB + kstep, voffB); PG8_STAGE(PG8_SA(1, 0), cA + kstep, voffA); PG8_STAGE(PG8_SB(1, 1), cB + hstep + kstep, voffB);
;         PG8_WAIT_V(6); PG8_BAR;
;     ...
;     for (;;) {
;         const bool has_next = S.next(ui + 1, nxt);
;         const char* nA = has_next ? (const char*)g.A + (size_t)nxt.pm * tstep : cA; const char* nB = has_next ? (const char*)g.Bt + (size_t)nxt.pn * tstep : cB;
;         for (int t = 0; t < nt; t += 2) {
.LBB0_345:
	s_mov_b64 s[20:21], 0x80
	s_add_i32 m0, s59, 0x18000
	v_lshl_add_u64 v[8:9], v[8:9], 0, s[20:21]
	s_waitcnt vmcnt(2)
	s_barrier
	global_load_lds_dwordx4 v[8:9], off
	v_lshl_add_u64 v[4:5], v[4:5], 0, s[20:21]
	s_add_i32 m0, s59, 0x1a000
	s_add_i32 s63, s59, 0x8000
	global_load_lds_dwordx4 v[4:5], off
	v_lshl_add_u64 v[4:5], v[6:7], 0, s[20:21]
	s_mov_b32 m0, s63
	s_add_i32 s64, s59, 0xa000
	global_load_lds_dwordx4 v[4:5], off
	v_lshl_add_u64 v[4:5], v[10:11], 0, s[20:21]
	s_mov_b32 m0, s64
	v_lshl_add_u64 v[2:3], v[2:3], 0, s[20:21]
	global_load_lds_dwordx4 v[4:5], off
	s_add_i32 m0, s59, 0x1c000
	v_lshl_add_u64 v[0:1], v[0:1], 0, s[20:21]
	global_load_lds_dwordx4 v[2:3], off
	s_add_i32 m0, s59, 0x1e000
	s_lshr_b32 s1, s1, 26
	global_load_lds_dwordx4 v[0:1], off
	s_and_b32 s2, s2, 3
	s_add_i32 s1, s0, s1
	s_ashr_i32 s65, s1, 6
	s_lshl_b32 s66, s3, 6
	s_lshl_b32 s1, s3, 13
	s_lshl_b32 s67, s2, 5
	s_cmp_gt_i32 s0, 63
	s_cselect_b64 s[22:23], -1, 0
	s_add_i32 s68, s65, -2
	s_cmpk_lt_u32 s11, 0x100
	s_cselect_b64 s[24:25], -1, 0
	s_add_u32 s69, s90, 0x9000000
	s_addc_u32 s70, s91, 0
	s_add_u32 s26, s90, 0x2600000
	s_addc_u32 s27, s91, 0
	s_add_u32 s28, s90, 0x3e00000
	s_addc_u32 s29, s91, 0
	s_add_u32 s30, s90, 0x2200000
	s_addc_u32 s31, s91, 0
	v_lshlrev_b32_e32 v1, 2, v201
	s_add_u32 s71, s88, 0x4000000
	v_lshl_or_b32 v0, v201, 6, v238
	v_and_b32_e32 v1, 32, v1
	s_addc_u32 s72, s89, 0
	v_bitop3_b32 v0, v0, s1, v1 bitop3:0xde
	s_add_u32 s34, s90, 0x20000
	v_add_u32_e32 v1, v237, v235
	s_addc_u32 s35, s91, 0
	v_mul_lo_u32 v1, s0, v1
	s_add_u32 s36, s90, 0x100000
	v_lshlrev_b32_e32 v1, 1, v1
	s_addc_u32 s37, s91, 0
	v_add3_u32 v136, v233, v1, v234
	v_add_u32_e32 v1, v236, v235
	s_cmp_gt_u32 s2, 1
	v_mul_lo_u32 v1, s0, v1
	s_waitcnt vmcnt(6)
	s_cselect_b64 s[38:39], -1, 0
	s_cmp_eq_u32 s2, 2
	v_lshlrev_b32_e32 v1, 1, v1
	v_lshl_or_b32 v170, s2, 12, v239
	s_cselect_b64 s[40:41], -1, 0
	v_lshl_add_u64 v[138:139], s[12:13], 0, v[136:137]
	v_add3_u32 v136, v233, v1, v234
	s_add_i32 s75, 0, 0x10000
	s_add_i32 s76, 0, 0x14000
	v_add_u32_e32 v173, 0, v0
	v_mbcnt_lo_u32_b32 v0, -1, 0
	s_ashr_i32 s73, s83, 31
	s_mov_b32 s86, s80
	s_ashr_i32 s74, s80, 31
	v_lshl_add_u64 v[140:141], s[12:13], 0, v[136:137]
	v_mov_b64_e32 v[142:143], 0xb80
	v_mov_b64_e32 v[144:145], 0xb7f
	v_add_u32_e32 v171, s75, v170
	v_add_u32_e32 v172, s76, v170
	s_movk_i32 s77, 0x300
	s_mov_b64 s[42:43], 0xcffe200
	s_mov_b32 s78, 0xcffe000
	v_mbcnt_hi_u32_b32 v174, -1, v0
	s_mov_b32 s79, 0
	s_barrier
	s_mov_b32 s98, 0
	s_mov_b32 s81, 0
	v_readfirstlane_b32 s80, v246
	s_or_b32 s98, s98, s80
	s_bcnt1_i32_b32 s80, s80
	s_cmp_lg_u32 s80, 1
	s_cselect_b32 s80, 1, 0
	s_or_b32 s81, s81, s80
	v_readfirstlane_b32 s80, v247
	s_or_b32 s98, s98, s80
	s_bcnt1_i32_b32 s80, s80
	s_cmp_lg_u32 s80, 1
	s_cselect_b32 s80, 1, 0
	s_or_b32 s81, s81, s80
	v_readfirstlane_b32 s80, v248
	s_or_b32 s98, s98, s80
	s_bcnt1_i32_b32 s80, s80
	s_cmp_lg_u32 s80, 1
	s_cselect_b32 s80, 1, 0
	s_or_b32 s81, s81, s80
	v_readfirstlane_b32 s80, v249
	s_or_b32 s98, s98, s80
	s_bcnt1_i32_b32 s80, s80
	s_cmp_lg_u32 s80, 1
	s_cselect_b32 s80, 1, 0
	s_or_b32 s81, s81, s80
	v_readfirstlane_b32 s80, v250
	s_or_b32 s98, s98, s80
	s_bcnt1_i32_b32 s80, s80
	s_cmp_lg_u32 s80, 1
	s_cselect_b32 s80, 1, 0
	s_or_b32 s81, s81, s80
	v_readfirstlane_b32 s80, v251
	s_or_b32 s98, s98, s80
	s_bcnt1_i32_b32 s80, s80
	s_cmp_lg_u32 s80, 1
	s_cselect_b32 s80, 1, 0
	s_or_b32 s81, s81, s80
	v_readfirstlane_b32 s80, v252
	s_or_b32 s98, s98, s80
	s_bcnt1_i32_b32 s80, s80
	s_cmp_lg_u32 s80, 1
	s_cselect_b32 s80, 1, 0
	s_or_b32 s81, s81, s80
	v_readfirstlane_b32 s80, v253
	s_or_b32 s98, s98, s80
	s_bcnt1_i32_b32 s80, s80
	s_cmp_lg_u32 s80, 1
	s_cselect_b32 s80, 1, 0
	s_or_b32 s81, s81, s80
	s_bcnt1_i32_b32 s80, s98
	s_cmp_lg_u32 s80, 8
	s_cselect_b32 s80, 1, 0
	s_or_b32 s98, s81, s80
	s_mov_b32 s99, 0
	s_branch .LBB0_348
